# idle-round capacity re-tune: 20 transposer items per wave in the layer-0 up-GEMM idle round, fewer in the layer-1 mixers hook
# baseline (speedup 1.0000x reference)
.LBB0_1179:
	s_waitcnt vmcnt(0)
	s_barrier
	s_cmp_lt_u32 s96, 128
	s_cbranch_scc1 .LBB0_1180
	s_load_dwordx2 s[0:1], s[92:93], 0x58
	s_load_dwordx2 s[2:3], s[92:93], 0xb8
	s_load_dwordx2 s[4:5], s[92:93], 0xc0
	s_load_dwordx2 s[6:7], s[92:93], 0xc8
	s_load_dwordx2 s[8:9], s[92:93], 0xd0
	s_load_dwordx2 s[10:11], s[92:93], 0xe8
	v_and_b32_e32 v74, 63, v154
	v_lshrrev_b32_e32 v75, 6, v154
	v_mul_u32_u24_e32 v75, 0x2100, v75
	v_lshrrev_b32_e32 v3, 5, v74
	v_and_b32_e32 v4, 31, v74
	v_lshlrev_b32_e32 v4, 2, v4
	v_lshrrev_b32_e32 v5, 3, v74
	v_and_b32_e32 v6, 7, v74
	v_mul_u32_u24_e32 v2, 264, v6
	v_add_u32_e32 v2, v2, v5
	v_lshl_add_u32 v2, v2, 2, v75
	v_lshlrev_b32_e32 v6, 4, v6
	v_mul_u32_u24_e32 v1, 132, v5
	v_add3_u32 v1, v1, v6, v75
	v_readfirstlane_b32 s13, v154
	s_lshr_b32 s13, s13, 6
	s_lshl_b32 s26, s96, 3
	s_add_u32 s13, s13, s26
	s_sub_u32 s12, s13, 1024
	s_add_u32 s12, s12, 33280
	s_waitcnt lgkmcnt(0)
	s_cmp_ge_u32 s12, 53760
	s_cbranch_scc1 .Ltrs_done
	s_cmp_ge_u32 s12, 33280
	s_cselect_b32 s41, 1, 0
	s_cselect_b32 s26, 33280, 0
	s_sub_u32 s42, s12, s26
	s_cmp_ge_u32 s42, 12288
	s_cbranch_scc1 .Ltrs_m2
	s_mul_i32 s43, s42, 43691
	s_lshr_b32 s43, s43, 24
	s_mul_i32 s26, s43, 384
	s_sub_u32 s44, s42, s26
	s_mov_b32 s14, s0
	s_mov_b32 s15, s1
	s_mov_b32 s36, 0xc000
	s_mov_b32 s37, 0x6000000
	s_mov_b32 s38, 0x0
	s_mov_b32 s39, 0x3000000
	s_mov_b32 s40, 0x1000
	s_branch .Ltrs_dec_done1

.Ltrs_loop:
	s_add_u32 s12, s12, 1024
	s_cmp_lt_u32 s12, 53760
	s_cselect_b32 s24, 1, 0
	s_cbranch_scc0 .Ltrs_nonext8
	s_cmp_ge_u32 s12, 33280
	s_cselect_b32 s41, 1, 0
	s_cselect_b32 s26, 33280, 0
	s_sub_u32 s42, s12, s26
	s_cmp_ge_u32 s42, 12288
	s_cbranch_scc1 .Ltrs_m11
	s_mul_i32 s43, s42, 43691
	s_lshr_b32 s43, s43, 24
	s_mul_i32 s26, s43, 384
	s_sub_u32 s44, s42, s26
	s_mov_b32 s16, s0
	s_mov_b32 s17, s1
	s_mov_b32 s36, 0xc000
	s_mov_b32 s37, 0x6000000
	s_mov_b32 s38, 0x0
	s_mov_b32 s39, 0x3000000
	s_mov_b32 s40, 0x1000
	s_branch .Ltrs_dec_done10

.Ltrs_after9:
	ds_write_b32 v1, v10 offset:0
	ds_write_b32 v1, v11 offset:4
	ds_write_b32 v1, v12 offset:8
	ds_write_b32 v1, v13 offset:12
	ds_write_b32 v1, v14 offset:1056
	ds_write_b32 v1, v15 offset:1060
	ds_write_b32 v1, v16 offset:1064
	ds_write_b32 v1, v17 offset:1068
	ds_write_b32 v1, v18 offset:2112
	ds_write_b32 v1, v19 offset:2116
	ds_write_b32 v1, v20 offset:2120
	ds_write_b32 v1, v21 offset:2124
	ds_write_b32 v1, v22 offset:3168
	ds_write_b32 v1, v23 offset:3172
	ds_write_b32 v1, v24 offset:3176
	ds_write_b32 v1, v25 offset:3180
	ds_write_b32 v1, v26 offset:4224
	ds_write_b32 v1, v27 offset:4228
	ds_write_b32 v1, v28 offset:4232
	ds_write_b32 v1, v29 offset:4236
	ds_write_b32 v1, v30 offset:5280
	ds_write_b32 v1, v31 offset:5284
	ds_write_b32 v1, v32 offset:5288
	ds_write_b32 v1, v33 offset:5292
	ds_write_b32 v1, v34 offset:6336
	ds_write_b32 v1, v35 offset:6340
	ds_write_b32 v1, v36 offset:6344
	ds_write_b32 v1, v37 offset:6348
	ds_write_b32 v1, v38 offset:7392
	ds_write_b32 v1, v39 offset:7396
	ds_write_b32 v1, v40 offset:7400
	ds_write_b32 v1, v41 offset:7404
	v_mad_u32_u24 v9, v5, s22, v6
	s_lshl_b32 s46, s22, 3
	s_waitcnt lgkmcnt(0)
	ds_read_b32 v74, v2 offset:0
	ds_read_b32 v75, v2 offset:132
	ds_read_b32 v76, v2 offset:264
	ds_read_b32 v77, v2 offset:396
	ds_read_b32 v78, v2 offset:528
	ds_read_b32 v79, v2 offset:660
	ds_read_b32 v80, v2 offset:792
	ds_read_b32 v81, v2 offset:924
	ds_read_b32 v82, v2 offset:32
	ds_read_b32 v83, v2 offset:164
	ds_read_b32 v84, v2 offset:296
	ds_read_b32 v85, v2 offset:428
	ds_read_b32 v86, v2 offset:560
	ds_read_b32 v87, v2 offset:692
	ds_read_b32 v88, v2 offset:824
	ds_read_b32 v89, v2 offset:956
	s_waitcnt lgkmcnt(8)
	v_cvt_pk_bf16_f32 v106, v74, v75
	v_cvt_pk_bf16_f32 v107, v76, v77
	v_cvt_pk_bf16_f32 v108, v78, v79
	v_cvt_pk_bf16_f32 v109, v80, v81
	global_store_dwordx4 v9, v[106:109], s[18:19]
	s_add_u32 s18, s18, s46
	s_addc_u32 s19, s19, 0
	ds_read_b32 v90, v2 offset:64
	ds_read_b32 v91, v2 offset:196
	ds_read_b32 v92, v2 offset:328
	ds_read_b32 v93, v2 offset:460
	ds_read_b32 v94, v2 offset:592
	ds_read_b32 v95, v2 offset:724
	ds_read_b32 v96, v2 offset:856
	ds_read_b32 v97, v2 offset:988
	s_waitcnt lgkmcnt(8)
	v_cvt_pk_bf16_f32 v110, v82, v83
	v_cvt_pk_bf16_f32 v111, v84, v85
	v_cvt_pk_bf16_f32 v112, v86, v87
	v_cvt_pk_bf16_f32 v113, v88, v89
	global_store_dwordx4 v9, v[110:113], s[18:19]
	s_add_u32 s18, s18, s46
	s_addc_u32 s19, s19, 0
	ds_read_b32 v98, v2 offset:96
	ds_read_b32 v99, v2 offset:228
	ds_read_b32 v100, v2 offset:360
	ds_read_b32 v101, v2 offset:492
	ds_read_b32 v102, v2 offset:624
	ds_read_b32 v103, v2 offset:756
	ds_read_b32 v104, v2 offset:888
	ds_read_b32 v105, v2 offset:1020
	s_waitcnt lgkmcnt(8)
	v_cvt_pk_bf16_f32 v106, v90, v91
	v_cvt_pk_bf16_f32 v107, v92, v93
	v_cvt_pk_bf16_f32 v108, v94, v95
	v_cvt_pk_bf16_f32 v109, v96, v97
	global_store_dwordx4 v9, v[106:109], s[18:19]
	s_add_u32 s18, s18, s46
	s_addc_u32 s19, s19, 0
	s_waitcnt lgkmcnt(0)
	v_cvt_pk_bf16_f32 v110, v98, v99
	v_cvt_pk_bf16_f32 v111, v100, v101
	v_cvt_pk_bf16_f32 v112, v102, v103
	v_cvt_pk_bf16_f32 v113, v104, v105
	global_store_dwordx4 v9, v[110:113], s[18:19]
	s_cmp_eq_u32 s24, 0
	s_cbranch_scc1 .Ltrs_done
	s_add_u32 s12, s12, 1024
	s_cmp_lt_u32 s12, 53760
	s_cselect_b32 s24, 1, 0
	s_cbranch_scc0 .Ltrs_nonext17
	s_cmp_ge_u32 s12, 33280
	s_cselect_b32 s41, 1, 0
	s_cselect_b32 s26, 33280, 0
	s_sub_u32 s42, s12, s26
	s_cmp_ge_u32 s42, 12288
	s_cbranch_scc1 .Ltrs_m20
	s_mul_i32 s43, s42, 43691
	s_lshr_b32 s43, s43, 24
	s_mul_i32 s26, s43, 384
	s_sub_u32 s44, s42, s26
	s_mov_b32 s14, s0
	s_mov_b32 s15, s1
	s_mov_b32 s36, 0xc000
	s_mov_b32 s37, 0x6000000
	s_mov_b32 s38, 0x0
	s_mov_b32 s39, 0x3000000
	s_mov_b32 s40, 0x1000
	s_branch .Ltrs_dec_done19

.LBB0_1734:
	s_cmp_lt_u32 s96, 128
	s_cbranch_scc1 .Lmix1_skip
	s_load_dwordx2 s[0:1], s[92:93], 0x58
	s_load_dwordx2 s[2:3], s[92:93], 0xb8
	s_load_dwordx2 s[4:5], s[92:93], 0xc0
	s_load_dwordx2 s[6:7], s[92:93], 0xc8
	s_load_dwordx2 s[8:9], s[92:93], 0xd0
	s_load_dwordx2 s[10:11], s[92:93], 0xe8
	v_and_b32_e32 v74, 63, v154
	v_lshrrev_b32_e32 v75, 6, v154
	v_mul_u32_u24_e32 v75, 0x2100, v75
	v_lshrrev_b32_e32 v3, 5, v74
	v_and_b32_e32 v4, 31, v74
	v_lshlrev_b32_e32 v4, 2, v4
	v_lshrrev_b32_e32 v5, 3, v74
	v_and_b32_e32 v6, 7, v74
	v_mul_u32_u24_e32 v2, 264, v6
	v_add_u32_e32 v2, v2, v5
	v_lshl_add_u32 v2, v2, 2, v75
	v_lshlrev_b32_e32 v6, 4, v6
	v_mul_u32_u24_e32 v1, 132, v5
	v_add3_u32 v1, v1, v6, v75
	v_readfirstlane_b32 s13, v154
	s_lshr_b32 s13, s13, 6
	s_lshl_b32 s26, s96, 3
	s_add_u32 s13, s13, s26
	s_sub_u32 s12, s13, 1024
	s_add_u32 s12, s12, 53760
	s_waitcnt lgkmcnt(0)
	s_cmp_ge_u32 s12, 60928
	s_cbranch_scc1 .Ltrn_done
	s_cmp_ge_u32 s12, 33280
	s_cselect_b32 s41, 1, 0
	s_cselect_b32 s26, 33280, 0
	s_sub_u32 s42, s12, s26
	s_cmp_ge_u32 s42, 12288
	s_cbranch_scc1 .Ltrn_m2
	s_mul_i32 s43, s42, 43691
	s_lshr_b32 s43, s43, 24
	s_mul_i32 s26, s43, 384
	s_sub_u32 s44, s42, s26
	s_mov_b32 s14, s0
	s_mov_b32 s15, s1
	s_mov_b32 s36, 0xc000
	s_mov_b32 s37, 0x6000000
	s_mov_b32 s38, 0x0
	s_mov_b32 s39, 0x3000000
	s_mov_b32 s40, 0x1000
	s_branch .Ltrn_dec_done1
